# phases 2/3: GEMM-first vs mixer-first workgroups chosen by blockIdx bit 3 (half of every XCD) instead of XCD parity (run 1)
# speedup vs baseline: 1.0085x; 1.0085x over previous
;     __device__ bool next(int i, Unit& u) const { const int L = i * G + c; if (L >= 256) return false; u.pm = L; u.pn = L >> 3; return true; }
; #define GATES_ROUNDS(R0, R1) do { pg8::Gemm g{(const bf16_t*)(ws + WS_XB), (const bf16_t*)(ws + WS_WIN) + (size_t)NPROJ * 1024, 1024, 1024, 1024}; pg8::RoundRange S; S.base.init(MROWS, 2048, G, bx); S.r0 = (R0); S.r1 = (R1); \
;         Epi<EM_GATES> E{ws, nullptr, nullptr, nullptr, nullptr, 0, lds}; pg8::gemm_phase(lds, g, S, E, wave); } while (0)
;     __device__ bool next(int i, Unit& u) const {
;         const long L = (long)i * G + c; if (L >= nwg) return false;
;         int wgid = (int)L; { const int q = nwg / NXCD, r = nwg % NXCD, xcd = wgid % NXCD, off = wgid / NXCD; wgid = (xcd < r ? xcd * (q + 1) : r * (q + 1) + (xcd - r) * q) + off; }
;         const int nig = WGM * nN, gid = wgid / nig, fm = gid * WGM, gsz = (nM - fm) < WGM ? (nM - fm) : WGM;
;         u.pm = fm + ((wgid % nig) % gsz); u.pn = (wgid % nig) / gsz; return true;
;     }
;     __device__ bool next(int i, Unit& u) const { if (r0 + i >= r1) return false; return base.next(r0 + i, u); }
; __global__ void __launch_bounds__(NTHR, 2) fwd_megakernel(Prm P) {
;     ...
;     const bool local_ok = __builtin_amdgcn_readfirstlane((int)__hip_atomic_load((unsigned*)(ws + WS_CTL) + XL_BAD, __ATOMIC_RELAXED, __HIP_MEMORY_SCOPE_AGENT)) == 0 && IN(0) && IN(2);
;     ...
;     if (IN(2)) {
;         if (bx & 1) GATES_ROUNDS(0, 2);
.LBB0_653:
	v_mov_b32_e32 v0, 0x1f60a000
	global_load_dword v0, v0, s[92:93] offset:2048 sc1
	v_readlane_b32 s4, v255, 3
	v_readlane_b32 s5, v255, 4
	s_cmp_lt_i32 s4, 3
	s_cselect_b64 s[4:5], -1, 0
	s_and_b64 s[18:19], s[4:5], s[76:77]
	v_readlane_b32 s6, v255, 5
	v_readlane_b32 s7, v255, 6
	s_andn2_b64 vcc, exec, s[18:19]
	s_waitcnt vmcnt(0)
	v_readfirstlane_b32 s2, v0
	s_nop 1
	v_writelane_b32 v255, s2, 15
	s_cbranch_vccnz .LBB0_735
	s_bitcmp0_b32 s66, 3
	s_cselect_b64 s[20:21], -1, 0
	s_and_b64 vcc, exec, s[20:21]
	s_cbranch_vccnz .LBB0_680
	v_readlane_b32 s2, v255, 9
	v_mbcnt_lo_u32_b32 v0, -1, 0
	v_mbcnt_hi_u32_b32 v0, -1, v0
	s_cmpk_gt_i32 s66, 0x3ff
	s_nop 0
	v_add_u32_e32 v8, s2, v0
	s_cbranch_scc1 .LBB0_680
	s_ashr_i32 s2, s66, 31
	s_lshr_b32 s4, s2, 29
	s_add_i32 s7, s66, s4
	s_and_b32 s4, s7, -8
	s_sub_i32 s8, s66, s4
	s_cmp_gt_i32 s8, -1
	s_cbranch_scc0 .LBB0_658
	s_lshl_b32 s6, s8, 7
	s_cbranch_execz .LBB0_659
	s_branch .LBB0_660

;     __device__ bool next(int i, Unit& u) const { const int L = i * G + c; if (L >= 256) return false; u.pm = L; u.pn = L >> 3; return true; }
; #define GATES_ROUNDS(R0, R1) do { pg8::Gemm g{(const bf16_t*)(ws + WS_XB), (const bf16_t*)(ws + WS_WIN) + (size_t)NPROJ * 1024, 1024, 1024, 1024}; pg8::RoundRange S; S.base.init(MROWS, 2048, G, bx); S.r0 = (R0); S.r1 = (R1); \
;         Epi<EM_GATES> E{ws, nullptr, nullptr, nullptr, nullptr, 0, lds}; pg8::gemm_phase(lds, g, S, E, wave); } while (0)
;     __device__ bool next(int i, Unit& u) const {
;         const long L = (long)i * G + c; if (L >= nwg) return false;
;         int wgid = (int)L; { const int q = nwg / NXCD, r = nwg % NXCD, xcd = wgid % NXCD, off = wgid / NXCD; wgid = (xcd < r ? xcd * (q + 1) : r * (q + 1) + (xcd - r) * q) + off; }
;         const int nig = WGM * nN, gid = wgid / nig, fm = gid * WGM, gsz = (nM - fm) < WGM ? (nM - fm) : WGM;
;         u.pm = fm + ((wgid % nig) % gsz); u.pn = (wgid % nig) / gsz; return true;
;     }
;     __device__ bool next(int i, Unit& u) const { if (r0 + i >= r1) return false; return base.next(r0 + i, u); }
; __global__ void __launch_bounds__(NTHR, 2) fwd_megakernel(Prm P) {
;     ...
;     if (IN(3)) {
;         if (!(bx & 1)) GATES_ROUNDS(2, 4);
.LBB0_791:
	v_readlane_b32 s8, v255, 3
	s_cmp_lt_i32 s8, 4
	s_cselect_b64 s[6:7], -1, 0
	s_and_b64 s[4:5], s[6:7], s[4:5]
	v_readlane_b32 s9, v255, 4
	v_readlane_b32 s10, v255, 5
	v_readlane_b32 s11, v255, 6
	v_writelane_b32 v255, s4, 16
	s_andn2_b64 vcc, exec, s[4:5]
	s_nop 0
	v_writelane_b32 v255, s5, 17
	s_cbranch_vccnz .LBB0_870
	s_bitcmp1_b32 s66, 3
	s_cselect_b64 s[4:5], -1, 0
	v_writelane_b32 v255, s4, 18
	s_and_b64 vcc, exec, s[4:5]
	s_nop 0
	v_writelane_b32 v255, s5, 19
	s_cbranch_vccnz .LBB0_811
	v_readlane_b32 s4, v255, 1
	v_readlane_b32 s5, v255, 2
	s_ashr_i32 s5, s4, 31
	s_lshl_b64 s[6:7], s[4:5], 1
	s_ashr_i32 s5, s66, 31
	v_mbcnt_lo_u32_b32 v0, -1, 0
	v_mbcnt_hi_u32_b32 v0, -1, v0
	v_readlane_b32 s2, v255, 9
	s_add_u32 s6, s6, s66
	s_addc_u32 s7, s7, s5
	v_add_u32_e32 v14, s2, v0
	v_mov_b64_e32 v[0:1], 0x3ff
	v_cmp_gt_i64_e32 vcc, s[6:7], v[0:1]
	s_cbranch_vccnz .LBB0_811
	s_ashr_i32 s2, s6, 31
	s_lshr_b32 s2, s2, 29
	s_add_i32 s8, s6, s2
	s_and_b32 s2, s8, -8
	s_sub_i32 s2, s6, s2
	s_cmp_gt_i32 s2, -1
	s_cbranch_scc0 .LBB0_796
	s_lshl_b32 s9, s2, 7
	s_ashr_i32 s6, s8, 3
	s_cbranch_execz .LBB0_797
	s_branch .LBB0_798
